# adds: both QK accumulator chains start from one -m prefilled block (first MFMA of chain B reads chain A's block as C before chain A overwrites it in order); 8 fewer v_mov_b64 per tile
# speedup vs baseline: 1.0801x; 1.0063x over previous
; #define MFMA32(a, b, c) __builtin_amdgcn_mfma_f32_32x32x16_bf16((a), (b), (c), 0, 0, 0)
; #define VLOAD(dst, sbv, q) do { _Pragma("unroll") for (int d_ = 0; d_ < 4; ++d_) dst[d_] = *(const lds_bf16x8*)((sbv) + vo[q] + d_ * 4096); } while (0)
; #define FENCE __builtin_amdgcn_sched_barrier(0)
; DI void diff_unit(KP p, int l, int b, int h, int qb, int isctx, float lamv, float lam_init, char* ldsc) {
;     ...
;     f32x16 st[2];
; #pragma unroll
;     for (int t = 0; t < 2; ++t)
; #pragma unroll
;       for (int ks = 0; ks < 4; ++ks) kf[t][ks] = *(const lds_bf16x8*)(sbk + ko[ks] + t * 4096);
;     FENCE;
;     pv_grp(o, vA, P[0]); pv_grp(o, vB, P[1]);
;     VLOAD(vA, sbv, 2); VLOAD(vB, sbv, 3);
;     FENCE;
; #pragma unroll
;     for (int i = 0; i < 16; ++i) { st[0][i] = 0.f; st[1][i] = 0.f; }
; #pragma unroll
;     for (int ks = 0; ks < 4; ++ks) st[0] = MFMA32(kf[0][ks], qf[ks], st[0]);
; #pragma unroll
;     for (int ks = 0; ks < 4; ++ks) st[1] = MFMA32(kf[1][ks], qf[ks], st[1]);
;     FENCE;
.LBB0_477:
	s_mov_b64 s[4:5], 0
	s_add_i32 s2, s17, 1
	s_and_b32 s16, s2, 3
	s_lshl_b32 s2, s16, 15
	s_add_i32 s15, s2, 0
	ds_read_b128 v[154:157], v136
	ds_read_b128 v[192:195], v136 offset:4096
	ds_read_b128 v[196:199], v137
	ds_read_b128 v[200:203], v137 offset:4096
	ds_read_b128 v[204:207], v138
	ds_read_b128 v[208:211], v138 offset:4096
	ds_read_b128 v[212:215], v139
	ds_read_b128 v[216:219], v139 offset:4096
	s_waitcnt lgkmcnt(8)
	v_mfma_f32_32x32x16_bf16 v[50:65], v[86:89], v[66:69], v[50:65]
	ds_read_b128 v[220:223], v248 offset:24576
	ds_read_b128 v[224:227], v248 offset:28672
	s_add_i32 s18, s3, 0xc0
	s_add_i32 s19, s10, 64
	s_cmp_eq_u32 s11, 0
	s_cselect_b32 s19, s18, s19
	s_mul_i32 s19, s19, 0x1600
	s_add_u32 s18, s22, s19
	s_addc_u32 s19, s23, 0
	s_add_i32 s24, s17, 3
	s_and_b32 s24, s24, 3
	s_lshl_b32 s24, s24, 15
	s_add_i32 s24, s13, s24
	s_mov_b32 m0, s24
	v_mfma_f32_32x32x16_bf16 v[34:49], v[82:85], v[66:69], v[34:49]
	global_load_lds_dwordx4 v244, s[18:19]
	s_add_i32 m0, s24, 0x2000
	v_mfma_f32_32x32x16_bf16 v[18:33], v[78:81], v[66:69], v[18:33]
	v_mfma_f32_32x32x16_bf16 v[2:17], v[74:77], v[66:69], v[2:17]
	v_mov_b64_e32 v[66:67], v[252:253]
	v_mov_b64_e32 v[68:69], v[252:253]
	v_mov_b64_e32 v[74:75], v[252:253]
	global_load_lds_dwordx4 v245, s[18:19]
	s_add_i32 m0, s24, 0x4000
	v_mfma_f32_32x32x16_bf16 v[50:65], v[126:129], v[70:73], v[50:65]
	v_mov_b64_e32 v[76:77], v[252:253]
	v_mov_b64_e32 v[78:79], v[252:253]
	v_mov_b64_e32 v[80:81], v[252:253]
	ds_read_b128 v[126:129], v248 offset:20480
	v_mfma_f32_32x32x16_bf16 v[34:49], v[122:125], v[70:73], v[34:49]
	ds_read_b128 v[122:125], v248 offset:16384
	ds_read_b128 v[228:231], v255 offset:16384
	ds_read_b128 v[232:235], v255 offset:20480
	ds_read_b128 v[236:239], v255 offset:24576
	ds_read_b128 v[240:243], v255 offset:28672
	v_mfma_f32_32x32x16_bf16 v[18:33], v[94:97], v[70:73], v[18:33]
	v_mfma_f32_32x32x16_bf16 v[2:17], v[90:93], v[70:73], v[2:17]
	v_mov_b64_e32 v[70:71], v[252:253]
	v_mov_b64_e32 v[72:73], v[252:253]
	global_load_lds_dwordx4 v246, s[20:21]
	s_add_i32 m0, s24, 0x6000
	s_waitcnt lgkmcnt(8)
	v_mfma_f32_32x32x16_bf16 v[82:97], v[154:157], v[98:101], v[66:81]
	v_mfma_f32_32x32x16_bf16 v[66:81], v[192:195], v[98:101], v[66:81]
	v_mfma_f32_32x32x16_bf16 v[66:81], v[200:203], v[102:105], v[66:81]
	v_mfma_f32_32x32x16_bf16 v[82:97], v[196:199], v[102:105], v[82:97]
	global_load_lds_dwordx4 v247, s[20:21]
	s_add_u32 s20, s20, 0x80
	s_addc_u32 s21, s21, 0
	v_mfma_f32_32x32x16_bf16 v[66:81], v[208:211], v[106:109], v[66:81]
	v_mfma_f32_32x32x16_bf16 v[82:97], v[204:207], v[106:109], v[82:97]
	v_mfma_f32_32x32x16_bf16 v[66:81], v[216:219], v[110:113], v[66:81]
	v_mfma_f32_32x32x16_bf16 v[82:97], v[212:215], v[110:113], v[82:97]
	s_waitcnt lgkmcnt(0)
	v_mfma_f32_32x32x16_bf16 v[50:65], v[122:125], v[118:121], v[50:65]
	v_add_u32_e32 v251, s15, v150
	v_add_u32_e32 v249, s15, v151
	s_add_i32 s18, s16, 1
	s_and_b32 s18, s18, 3
	s_lshl_b32 s18, s18, 15
	s_add_i32 s18, s18, s14
	v_add_u32_e32 v136, s18, v141
	v_add_u32_e32 v137, s18, v145
	v_add_u32_e32 v138, s18, v147
	v_add_u32_e32 v139, s18, v148
	s_lshl_b32 s19, s16, 15
	v_add_u32_e32 v248, s19, v149
	v_add_u32_e32 v255, s19, v146
	v_mfma_f32_32x32x16_bf16 v[34:49], v[126:129], v[118:121], v[34:49]
	v_exp_f32_e32 v122, v82
	v_exp_f32_e32 v124, v83
	v_exp_f32_e32 v126, v84
	v_exp_f32_e32 v128, v85
	v_exp_f32_e32 v156, v86
	v_mfma_f32_32x32x16_bf16 v[18:33], v[220:223], v[118:121], v[18:33]
	v_exp_f32_e32 v192, v87
	v_exp_f32_e32 v194, v88
	v_exp_f32_e32 v196, v89
	v_exp_f32_e32 v123, v90
	v_exp_f32_e32 v125, v91
	v_mfma_f32_32x32x16_bf16 v[2:17], v[224:227], v[118:121], v[2:17]
	v_exp_f32_e32 v127, v92
	v_exp_f32_e32 v129, v93
	v_exp_f32_e32 v157, v94
	v_exp_f32_e32 v193, v95
	v_exp_f32_e32 v195, v96
	v_mfma_f32_32x32x16_bf16 v[50:65], v[228:231], v[114:117], v[50:65]
	v_exp_f32_e32 v197, v97
	v_exp_f32_e32 v83, v66
	v_exp_f32_e32 v67, v67
	v_exp_f32_e32 v85, v68
	v_exp_f32_e32 v69, v69
	v_mfma_f32_32x32x16_bf16 v[34:49], v[232:235], v[114:117], v[34:49]
	v_exp_f32_e32 v87, v70
	v_exp_f32_e32 v71, v71
	v_exp_f32_e32 v89, v72
	v_exp_f32_e32 v73, v73
	v_pk_add_f32 v[92:93], v[124:125], v[122:123]
	v_pk_add_f32 v[92:93], v[126:127], v[92:93]
	v_mfma_f32_32x32x16_bf16 v[18:33], v[236:239], v[114:117], v[18:33]
	v_exp_f32_e32 v82, v74
	v_exp_f32_e32 v66, v75
	v_exp_f32_e32 v84, v76
	v_exp_f32_e32 v68, v77
	v_pk_add_f32 v[92:93], v[128:129], v[92:93]
	v_pk_add_f32 v[92:93], v[156:157], v[92:93]
	v_mfma_f32_32x32x16_bf16 v[2:17], v[240:243], v[114:117], v[2:17]
	v_exp_f32_e32 v86, v78
	v_exp_f32_e32 v70, v79
	v_exp_f32_e32 v88, v80
	v_exp_f32_e32 v72, v81
	v_pk_add_f32 v[92:93], v[192:193], v[92:93]
	v_pk_add_f32 v[92:93], v[194:195], v[92:93]
	v_pk_add_f32 v[92:93], v[196:197], v[92:93]
	ds_read_b128 v[78:81], v251 offset:24576
	ds_read_b128 v[74:77], v251 offset:28672
	v_pk_add_f32 v[198:199], v[66:67], v[82:83]
	v_pk_add_f32 v[198:199], v[84:85], v[198:199]
	v_pk_add_f32 v[198:199], v[68:69], v[198:199]
	v_pk_add_f32 v[198:199], v[86:87], v[198:199]
	v_pk_add_f32 v[198:199], v[70:71], v[198:199]
	v_pk_add_f32 v[198:199], v[88:89], v[198:199]
	v_pk_add_f32 v[198:199], v[72:73], v[198:199]
	v_pk_add_f32 v[198:199], v[198:199], v[92:93]
	v_max_f32_e32 v200, v198, v199
	v_cmp_lt_f32_e32 vcc, 0x43000000, v200
	s_cmp_lg_u64 vcc, 0
	s_cbranch_scc1 .Ldiff_rare
